# mlstm_seq: LDS staging of the next chunk after the output section; P5 late copy on four-tile workgroups
# speedup vs baseline: 1.0104x; 1.0104x over previous
; #define LAS __attribute__((address_space(3)))
; __device__ __forceinline__ float bflo(unsigned w) { return __uint_as_float(w << 16); }
; __device__ __forceinline__ float bfhi(unsigned w) { return __uint_as_float(w & 0xffff0000u); }
; __device__ __forceinline__ unsigned pk2(float lo, float hi) { return pg8::cvt_pk_bf16(lo, hi); }
; __device__ __forceinline__ void mlstm_seq(LAS unsigned char* lds, int tid_in, int b, int h, const bf16_t* z1, const bf16_t* z2a, const float* g_hnorm, bf16_t* yb, const unsigned char* ws) {
;     ...
;         for (int i = 0; i < 2; ++i) { *(LAS u32x4*)(Qb + (srow + 32 * i) * QS + sc16 * 16) = pq[i]; *(LAS u32x4*)(KUb + (srow + 32 * i) * US + sc16 * 16) = pk[i]; }
; #pragma unroll
;         for (int i = 0; i < 4; ++i) *(LAS u32x4*)(Vb + (vrow + 16 * i) * VS + vc * 16) = pv[i];
;         *(LAS u32x4*)(SCb + (tid >> 3) * SS + (tid & 7) * 16) = psc;
;     ...
;         if (tid < 128) NV[tid] = decay * NV[tid] + dn;
; #pragma unroll
;         for (int tb = 0; tb < 2; ++tb) {
;             const int t = 32 * tb + r;
;             const float inv = INV[t];
;             const f32x4 pa = *(const LAS f32x4*)(PR + t * 8), pb = *(const LAS f32x4*)(PR + t * 8 + 4);
;             const float rn = inv * rsqrtf(inv * inv * ((pa[0] + pa[1]) + (pa[2] + pa[3]) + (pb[0] + pb[1]) + (pb[2] + pb[3])) * (1.f / 256.f) + EPSN);
; #pragma unroll
;             for (int g = 0; g < 4; ++g) {
;                 const int dv = 32 * wid + 8 * g + 4 * hh;
;                 u32x2 w; w.x = pk2(Z[tb][4 * g] * rn * bflo(zo[tb][g].x), Z[tb][4 * g + 1] * rn * bfhi(zo[tb][g].x));
;                 w.y = pk2(Z[tb][4 * g + 2] * rn * bflo(zo[tb][g].y), Z[tb][4 * g + 3] * rn * bfhi(zo[tb][g].y));
;                 *(u32x2*)(yb + (tok0 + t) * Z2_LD + h * 256 + dv) = w;
;             }
;         }
.Lml_nvskip:
	s_or_b64 exec, exec, s[12:13]
	s_add_u32 s8, s8, 4
	s_addc_u32 s9, s9, 0
	s_mov_b64 s[16:17], 0x800
	s_waitcnt lgkmcnt(0)
	v_mul_f32_e32 v140, v226, v226
	v_add_f32_e32 v141, v223, v222
	v_add_f32_e32 v142, v224, v225
	v_add_f32_e32 v143, v232, v233
	v_add_f32_e32 v146, v230, v231
	v_add_f32_e32 v141, v141, v142
	v_add_f32_e32 v141, v141, v146
	v_add_f32_e32 v141, v143, v141
	v_mul_f32_e32 v141, v140, v141
	v_fmamk_f32 v141, v141, 0x3b800000, v221
	v_mul_f32_e32 v142, 0x4b800000, v141
	v_cmp_gt_f32_e32 vcc, s77, v141
	s_nop 1
	v_cndmask_b32_e32 v141, v141, v142, vcc
	v_rsq_f32_e32 v141, v141
	s_nop 0
	v_mul_f32_e32 v142, 0x45800000, v141
	v_cndmask_b32_e32 v141, v141, v142, vcc
	v_mul_f32_e32 v145, v226, v141
	v_mul_f32_e32 v82, v82, v145
	v_lshlrev_b32_e32 v140, 16, v180
	v_mul_f32_e32 v83, v83, v145
	v_and_b32_e32 v141, 0xffff0000, v180
	v_mul_f32_e32 v82, v82, v140
	v_mul_f32_e32 v83, v83, v141
	v_mul_f32_e32 v84, v84, v145
	v_lshlrev_b32_e32 v142, 16, v181
	v_mul_f32_e32 v85, v85, v145
	v_and_b32_e32 v143, 0xffff0000, v181
	v_mul_f32_e32 v84, v84, v142
	v_mul_f32_e32 v85, v85, v143
	v_mul_f32_e32 v86, v86, v145
	v_lshlrev_b32_e32 v140, 16, v178
	v_mul_f32_e32 v87, v87, v145
	v_and_b32_e32 v141, 0xffff0000, v178
	v_mul_f32_e32 v86, v86, v140
	v_mul_f32_e32 v87, v87, v141
	v_mul_f32_e32 v88, v88, v145
	v_lshlrev_b32_e32 v142, 16, v179
	v_mul_f32_e32 v89, v89, v145
	v_and_b32_e32 v143, 0xffff0000, v179
	v_mul_f32_e32 v88, v88, v142
	v_mul_f32_e32 v89, v89, v143
	v_cvt_pk_bf16_f32 v82, v82, v83
	v_cvt_pk_bf16_f32 v83, v84, v85
	v_cvt_pk_bf16_f32 v84, v86, v87
	v_cvt_pk_bf16_f32 v85, v88, v89
	s_nop 1
	v_permlane32_swap_b32_e32 v82, v84
	v_permlane32_swap_b32_e32 v83, v85
	v_mul_f32_e32 v90, v90, v145
	v_lshlrev_b32_e32 v140, 16, v174
	v_mul_f32_e32 v91, v91, v145
	v_and_b32_e32 v141, 0xffff0000, v174
	v_mul_f32_e32 v90, v90, v140
	v_mul_f32_e32 v91, v91, v141
	v_mul_f32_e32 v92, v92, v145
	v_lshlrev_b32_e32 v142, 16, v175
	v_mul_f32_e32 v93, v93, v145
	v_and_b32_e32 v143, 0xffff0000, v175
	v_mul_f32_e32 v92, v92, v142
	v_mul_f32_e32 v93, v93, v143
	v_mul_f32_e32 v94, v94, v145
	v_lshlrev_b32_e32 v140, 16, v166
	v_mul_f32_e32 v95, v95, v145
	v_and_b32_e32 v141, 0xffff0000, v166
	v_mul_f32_e32 v94, v94, v140
	v_mul_f32_e32 v95, v95, v141
	v_mul_f32_e32 v96, v96, v145
	v_lshlrev_b32_e32 v142, 16, v167
	v_mul_f32_e32 v97, v97, v145
	v_and_b32_e32 v143, 0xffff0000, v167
	v_mul_f32_e32 v96, v96, v142
	v_mul_f32_e32 v97, v97, v143
	v_cvt_pk_bf16_f32 v90, v90, v91
	v_cvt_pk_bf16_f32 v91, v92, v93
	v_cvt_pk_bf16_f32 v92, v94, v95
	v_cvt_pk_bf16_f32 v93, v96, v97
	s_nop 1
	v_permlane32_swap_b32_e32 v90, v92
	v_permlane32_swap_b32_e32 v91, v93
	s_nop 0
	v_permlane16_swap_b32_e32 v82, v90
	v_permlane16_swap_b32_e32 v83, v91
	v_permlane16_swap_b32_e32 v84, v92
	v_permlane16_swap_b32_e32 v85, v93
	s_add_u32 s12, s66, 0x10800000
	s_addc_u32 s13, s67, 0
	global_store_dwordx4 v168, v[82:85], s[12:13]
	s_add_u32 s12, s66, 0x10820000
	s_addc_u32 s13, s67, 0
	global_store_dwordx4 v168, v[90:93], s[12:13]
	v_mul_f32_e32 v140, v227, v227
	v_add_f32_e32 v141, v235, v234
	v_add_f32_e32 v142, v236, v237
	v_add_f32_e32 v143, v248, v249
	v_add_f32_e32 v146, v246, v247
	v_add_f32_e32 v141, v141, v142
	v_add_f32_e32 v141, v141, v146
	v_add_f32_e32 v141, v143, v141
	v_mul_f32_e32 v141, v140, v141
	v_fmamk_f32 v141, v141, 0x3b800000, v221
	v_mul_f32_e32 v142, 0x4b800000, v141
	v_cmp_gt_f32_e32 vcc, s77, v141
	s_nop 1
	v_cndmask_b32_e32 v141, v141, v142, vcc
	v_rsq_f32_e32 v141, v141
	s_nop 0
	v_mul_f32_e32 v142, 0x45800000, v141
	v_cndmask_b32_e32 v141, v141, v142, vcc
	v_mul_f32_e32 v145, v227, v141
	v_mul_f32_e32 v66, v66, v145
	v_lshlrev_b32_e32 v140, 16, v158
	v_mul_f32_e32 v67, v67, v145
	v_and_b32_e32 v141, 0xffff0000, v158
	v_mul_f32_e32 v66, v66, v140
	v_mul_f32_e32 v67, v67, v141
	v_mul_f32_e32 v68, v68, v145
	v_lshlrev_b32_e32 v142, 16, v159
	v_mul_f32_e32 v69, v69, v145
	v_and_b32_e32 v143, 0xffff0000, v159
	v_mul_f32_e32 v68, v68, v142
	v_mul_f32_e32 v69, v69, v143
	v_mul_f32_e32 v70, v70, v145
	v_lshlrev_b32_e32 v140, 16, v156
	v_mul_f32_e32 v71, v71, v145
	v_and_b32_e32 v141, 0xffff0000, v156
	v_mul_f32_e32 v70, v70, v140
	v_mul_f32_e32 v71, v71, v141
	v_mul_f32_e32 v72, v72, v145
	v_lshlrev_b32_e32 v142, 16, v157
	v_mul_f32_e32 v73, v73, v145
	v_and_b32_e32 v143, 0xffff0000, v157
	v_mul_f32_e32 v72, v72, v142
	v_mul_f32_e32 v73, v73, v143
	v_cvt_pk_bf16_f32 v66, v66, v67
	v_cvt_pk_bf16_f32 v67, v68, v69
	v_cvt_pk_bf16_f32 v68, v70, v71
	v_cvt_pk_bf16_f32 v69, v72, v73
	s_nop 1
	v_permlane32_swap_b32_e32 v66, v68
	v_permlane32_swap_b32_e32 v67, v69
	v_mul_f32_e32 v74, v74, v145
	v_lshlrev_b32_e32 v140, 16, v154
	v_mul_f32_e32 v75, v75, v145
	v_and_b32_e32 v141, 0xffff0000, v154
	v_mul_f32_e32 v74, v74, v140
	v_mul_f32_e32 v75, v75, v141
	v_mul_f32_e32 v76, v76, v145
	v_lshlrev_b32_e32 v142, 16, v155
	v_mul_f32_e32 v77, v77, v145
	v_and_b32_e32 v143, 0xffff0000, v155
	v_mul_f32_e32 v76, v76, v142
	v_mul_f32_e32 v77, v77, v143
	v_mul_f32_e32 v78, v78, v145
	v_lshlrev_b32_e32 v140, 16, v152
	v_mul_f32_e32 v79, v79, v145
	v_and_b32_e32 v141, 0xffff0000, v152
	v_mul_f32_e32 v78, v78, v140
	v_mul_f32_e32 v79, v79, v141
	v_mul_f32_e32 v80, v80, v145
	v_lshlrev_b32_e32 v142, 16, v153
	v_mul_f32_e32 v81, v81, v145
	v_and_b32_e32 v143, 0xffff0000, v153
	v_mul_f32_e32 v80, v80, v142
	v_mul_f32_e32 v81, v81, v143
	v_cvt_pk_bf16_f32 v74, v74, v75
	v_cvt_pk_bf16_f32 v75, v76, v77
	v_cvt_pk_bf16_f32 v76, v78, v79
	v_cvt_pk_bf16_f32 v77, v80, v81
	s_nop 1
	v_permlane32_swap_b32_e32 v74, v76
	v_permlane32_swap_b32_e32 v75, v77
	s_nop 0
	v_permlane16_swap_b32_e32 v66, v74
	v_permlane16_swap_b32_e32 v67, v75
	v_permlane16_swap_b32_e32 v68, v76
	v_permlane16_swap_b32_e32 v69, v77
	s_add_u32 s12, s66, 0x10840000
	s_addc_u32 s13, s67, 0
	global_store_dwordx4 v168, v[66:69], s[12:13]
	s_add_u32 s12, s66, 0x10860000
	s_addc_u32 s13, s67, 0
	global_store_dwordx4 v168, v[74:77], s[12:13]
	s_mov_b64 s[12:13], 0x80000
	v_lshl_add_u64 v[160:161], v[160:161], 0, s[92:93]
	v_lshl_add_u64 v[162:163], v[162:163], 0, s[94:95]
	v_lshl_add_u64 v[150:151], v[150:151], 0, s[12:13]
	v_lshl_add_u64 v[172:173], v[172:173], 0, s[12:13]
	v_lshl_add_u64 v[168:169], v[168:169], 0, s[12:13]
	s_mov_b64 s[12:13], 0x68000
	v_lshl_add_u64 v[170:171], v[170:171], 0, s[16:17]
	v_lshl_add_u64 v[176:177], v[176:177], 0, s[12:13]
	s_cmp_eq_u32 s14, 1
	s_cbranch_scc1 .Lml_nostage
	s_waitcnt vmcnt(11)
	ds_write_b128 v0, v[98:101]
	ds_write_b128 v206, v[102:105] offset:17408
	ds_write_b128 v0, v[106:109] offset:8704
	ds_write_b128 v206, v[110:113] offset:27648
	ds_write_b128 v202, v[114:117] offset:37888
	ds_write_b128 v202, v[118:121] offset:47104
	ds_write_b128 v202, v[122:125] offset:56320
	ds_write_b128 v203, v[126:129] offset:27648
	ds_write_b128 v207, v[130:133]
; __device__ __forceinline__ void mlstm_seq(LAS unsigned char* lds, int tid_in, int b, int h, const bf16_t* z1, const bf16_t* z2a, const float* g_hnorm, bf16_t* yb, const unsigned char* ws) {
;     ...
;         u32x2 zo[2][4];
; #pragma unroll
;         for (int tb = 0; tb < 2; ++tb)
; #pragma unroll
;             for (int g = 0; g < 4; ++g) zo[tb][g] = pzo[tb][g];
;         const float wi0 = pwi0, wi1 = pwi1, wq = pwq, eq = peq, dq0 = pdq, dn = pdn;
;         __syncthreads();
.Lml_nostage:
	s_add_i32 s14, s14, -1
	s_waitcnt vmcnt(4)
	v_permlane16_swap_b32_e32 v182, v186
	v_permlane16_swap_b32_e32 v183, v187
	v_permlane16_swap_b32_e32 v184, v188
	v_permlane16_swap_b32_e32 v185, v189
	v_permlane16_swap_b32_e32 v190, v194
	v_permlane16_swap_b32_e32 v191, v195
	v_permlane16_swap_b32_e32 v192, v196
	v_permlane16_swap_b32_e32 v193, v197
	v_permlane32_swap_b32_e32 v182, v184
	v_permlane32_swap_b32_e32 v183, v185
	v_permlane32_swap_b32_e32 v186, v188
	v_permlane32_swap_b32_e32 v187, v189
	v_permlane32_swap_b32_e32 v190, v192
	v_permlane32_swap_b32_e32 v191, v193
	v_permlane32_swap_b32_e32 v194, v196
	v_permlane32_swap_b32_e32 v195, v197
	v_mov_b64_e32 v[180:181], v[182:183]
	v_mov_b64_e32 v[178:179], v[184:185]
	v_mov_b64_e32 v[174:175], v[186:187]
	v_mov_b64_e32 v[166:167], v[188:189]
	v_mov_b64_e32 v[158:159], v[190:191]
	v_mov_b64_e32 v[156:157], v[192:193]
	v_mov_b64_e32 v[154:155], v[194:195]
	v_mov_b64_e32 v[152:153], v[196:197]
	v_mov_b32_e32 v250, v217
	v_mov_b32_e32 v251, v218
	v_mov_b32_e32 v216, v219
	v_mov_b32_e32 v164, v215
	s_cmp_eq_u32 s14, 0
	s_cbranch_scc1 .LBB0_93
	s_waitcnt lgkmcnt(0)
	s_barrier
	s_branch .Lml_loop
